# attention softmax: sub+mul(log2e) folded into one fma per element (f32), -m*log2e formed once per key tile
# baseline (speedup 1.0000x reference)
.LBB0_935:
	s_mov_b64 s[8:9], s[4:5]
	s_add_u32 s4, s8, 1
	s_addc_u32 s5, s9, 0
	s_cmp_ge_u32 s4, s11
	s_cselect_b64 s[6:7], -1, 0
	s_cmp_lt_u32 s4, s11
	s_cselect_b64 s[12:13], -1, 0
	v_cndmask_b32_e64 v32, 0, 1, s[12:13]
	v_mov_b32_e32 v33, s89
	v_lshl_add_u64 v[32:33], s[8:9], 0, v[32:33]
	v_lshlrev_b64 v[34:35], 16, v[32:33]
	v_lshl_add_u64 v[34:35], v[90:91], 0, v[34:35]
	v_lshlrev_b32_e32 v136, 6, v32
	s_waitcnt lgkmcnt(0)
	s_barrier
	s_waitcnt vmcnt(1)
	ds_write_b128 v94, v[80:83] offset:8192
	s_waitcnt vmcnt(0)
	ds_write_b128 v94, v[84:87] offset:17408
	s_waitcnt lgkmcnt(0)
	s_barrier
	v_lshl_add_u64 v[32:33], v[136:137], 1, v[92:93]
	global_load_dwordx4 v[80:83], v[34:35], off
	global_load_dwordx4 v[84:87], v[32:33], off
	v_cmp_le_i32_e32 vcc, s10, v98
	s_and_saveexec_b64 s[8:9], vcc
	s_cbranch_execz .LBB0_934
	ds_read_b128 v[32:35], v101 offset:8192
	ds_read_b128 v[36:39], v101 offset:8224
	v_add_u32_e32 v130, s10, v95
	v_cmp_le_i32_e32 vcc, v130, v96
	v_add_u32_e32 v131, 2, v130
	s_waitcnt lgkmcnt(1)
	v_mfma_f32_32x32x16_bf16 v[48:63], v[32:35], v[72:75], 0
	ds_read_b128 v[32:35], v101 offset:8256
	ds_read_b128 v[106:109], v101 offset:8288
	v_add_u32_e32 v132, 3, v130
	v_add_u32_e32 v133, 8, v130
	v_add_u32_e32 v134, 9, v130
	s_mov_b32 s12, 0xf149f2ca
	s_waitcnt lgkmcnt(2)
	v_mfma_f32_32x32x16_bf16 v[48:63], v[36:39], v[64:67], v[48:63]
	s_waitcnt lgkmcnt(1)
	v_mfma_f32_32x32x16_bf16 v[48:63], v[32:35], v[68:71], v[48:63]
	ds_read_b128 v[32:35], v101 offset:12800
	ds_read_b128 v[110:113], v101 offset:12832
	ds_read_b128 v[114:117], v101 offset:12864
	ds_read_b128 v[118:121], v101 offset:12896
	ds_read_b128 v[122:125], v104
	ds_read_b128 v[126:129], v104 offset:32
	s_waitcnt lgkmcnt(6)
	v_mfma_f32_32x32x16_bf16 v[48:63], v[106:109], v[76:79], v[48:63]
	s_waitcnt lgkmcnt(5)
	v_mfma_f32_32x32x16_bf16 v[32:47], v[32:35], v[72:75], 0
	s_nop 9
	v_add_f32_e32 v48, v97, v48
	v_add_f32_e32 v49, v97, v49
	s_waitcnt lgkmcnt(1)
	v_sub_f32_e32 v48, v48, v122
	v_add_f32_e32 v50, v97, v50
	v_sub_f32_e32 v49, v49, v123
	v_cndmask_b32_e32 v106, v187, v48, vcc
	v_cmp_lt_i32_e32 vcc, v130, v96
	v_add_f32_e32 v51, v97, v51
	v_sub_f32_e32 v50, v50, v124
	v_cndmask_b32_e32 v107, v187, v49, vcc
	v_cmp_le_i32_e32 vcc, v131, v96
	v_add_f32_e32 v52, v97, v52
	v_sub_f32_e32 v51, v51, v125
	v_cndmask_b32_e32 v108, v187, v50, vcc
	v_cmp_le_i32_e32 vcc, v132, v96
	v_add_f32_e32 v53, v97, v53
	s_waitcnt lgkmcnt(0)
	v_sub_f32_e32 v52, v52, v126
	v_cndmask_b32_e32 v109, v187, v51, vcc
	v_cmp_le_i32_e32 vcc, v133, v96
	v_sub_f32_e32 v53, v53, v127
	v_add_f32_e32 v49, v97, v54
	v_cndmask_b32_e32 v122, v187, v52, vcc
	v_cmp_le_i32_e32 vcc, v134, v96
	v_add_u32_e32 v50, 10, v130
	v_sub_f32_e32 v49, v49, v128
	v_cndmask_b32_e32 v123, v187, v53, vcc
	v_cmp_le_i32_e32 vcc, v50, v96
	v_max3_f32 v48, v106, s12, v107
	v_mfma_f32_32x32x16_bf16 v[32:47], v[110:113], v[64:67], v[32:47]
	v_cndmask_b32_e32 v110, v187, v49, vcc
	v_add_f32_e32 v49, v97, v55
	v_add_u32_e32 v50, 11, v130
	v_max3_f32 v48, v48, v108, v109
	v_sub_f32_e32 v49, v49, v129
	v_cmp_le_i32_e32 vcc, v50, v96
	v_max3_f32 v48, v48, v122, v123
	v_add_u32_e32 v113, 16, v130
	v_cndmask_b32_e32 v111, v187, v49, vcc
	v_max3_f32 v112, v48, v110, v111
	ds_read_b128 v[48:51], v104 offset:64
	ds_read_b128 v[52:55], v104 offset:96
	v_add_f32_e32 v56, v97, v56
	v_cmp_le_i32_e32 vcc, v113, v96
	v_mfma_f32_32x32x16_bf16 v[32:47], v[114:117], v[68:71], v[32:47]
	s_waitcnt lgkmcnt(1)
	v_sub_f32_e32 v48, v56, v48
	v_cndmask_b32_e32 v56, v187, v48, vcc
	v_add_f32_e32 v48, v97, v57
	v_sub_f32_e32 v48, v48, v49
	v_add_u32_e32 v49, 17, v130
	v_cmp_le_i32_e32 vcc, v49, v96
	v_add_f32_e32 v49, v97, v58
	v_sub_f32_e32 v49, v49, v50
	v_add_u32_e32 v50, 18, v130
	v_cndmask_b32_e32 v57, v187, v48, vcc
	v_cmp_le_i32_e32 vcc, v50, v96
	v_add_u32_e32 v50, 19, v130
	v_max3_f32 v48, v112, v56, v57
	v_cndmask_b32_e32 v58, v187, v49, vcc
	v_add_f32_e32 v49, v97, v59
	v_sub_f32_e32 v49, v49, v51
	v_cmp_le_i32_e32 vcc, v50, v96
	v_add_f32_e32 v50, v97, v60
	s_waitcnt lgkmcnt(0)
	v_sub_f32_e32 v50, v50, v52
	v_cndmask_b32_e32 v59, v187, v49, vcc
	v_add_u32_e32 v49, 24, v130
	v_cmp_le_i32_e32 vcc, v49, v96
	v_add_f32_e32 v49, v97, v61
	v_sub_f32_e32 v49, v49, v53
	v_cndmask_b32_e32 v60, v187, v50, vcc
	v_add_u32_e32 v50, 25, v130
	v_cmp_le_i32_e32 vcc, v50, v96
	v_max3_f32 v48, v48, v58, v59
	v_mfma_f32_32x32x16_bf16 v[32:47], v[118:121], v[76:79], v[32:47]
	v_cndmask_b32_e32 v61, v187, v49, vcc
	v_max3_f32 v52, v48, v60, v61
	v_add_f32_e32 v48, v97, v62
	v_add_u32_e32 v49, 26, v130
	v_sub_f32_e32 v48, v48, v54
	v_cmp_le_i32_e32 vcc, v49, v96
	v_add_u32_e32 v49, 27, v130
	v_add_u32_e32 v113, 32, v130
	v_cndmask_b32_e32 v62, v187, v48, vcc
	v_add_f32_e32 v48, v97, v63
	v_sub_f32_e32 v48, v48, v55
	v_cmp_le_i32_e32 vcc, v49, v96
	v_add_f32_e32 v32, v97, v32
	v_add_f32_e32 v40, v97, v40
	v_cndmask_b32_e32 v63, v187, v48, vcc
	ds_read_b128 v[48:51], v104 offset:128
	v_max3_f32 v112, v52, v62, v63
	ds_read_b128 v[52:55], v104 offset:160
	v_cmp_le_i32_e32 vcc, v113, v96
	v_add_u32_e32 v113, 48, v130
	s_waitcnt lgkmcnt(1)
	v_sub_f32_e32 v32, v32, v48
	v_cndmask_b32_e32 v48, v187, v32, vcc
	v_add_f32_e32 v32, v97, v33
	v_add_u32_e32 v33, 33, v130
	v_sub_f32_e32 v32, v32, v49
	v_cmp_le_i32_e32 vcc, v33, v96
	v_add_f32_e32 v33, v97, v34
	v_add_u32_e32 v34, 34, v130
	v_cndmask_b32_e32 v49, v187, v32, vcc
	v_sub_f32_e32 v33, v33, v50
	v_cmp_le_i32_e32 vcc, v34, v96
	v_add_u32_e32 v34, 35, v130
	v_max3_f32 v32, v112, v48, v49
	v_cndmask_b32_e32 v50, v187, v33, vcc
	v_add_f32_e32 v33, v97, v35
	v_sub_f32_e32 v33, v33, v51
	v_cmp_le_i32_e32 vcc, v34, v96
	v_add_f32_e32 v34, v97, v36
	s_waitcnt lgkmcnt(0)
	v_sub_f32_e32 v34, v34, v52
	v_cndmask_b32_e32 v51, v187, v33, vcc
	v_add_u32_e32 v33, 40, v130
	v_cmp_le_i32_e32 vcc, v33, v96
	v_add_f32_e32 v33, v97, v37
	v_sub_f32_e32 v33, v33, v53
	v_cndmask_b32_e32 v52, v187, v34, vcc
	v_add_u32_e32 v34, 41, v130
	v_cmp_le_i32_e32 vcc, v34, v96
	v_max3_f32 v32, v32, v50, v51
	s_nop 0
	v_cndmask_b32_e32 v53, v187, v33, vcc
	v_max3_f32 v36, v32, v52, v53
	v_add_f32_e32 v32, v97, v38
	v_add_u32_e32 v33, 42, v130
	v_sub_f32_e32 v32, v32, v54
	v_cmp_le_i32_e32 vcc, v33, v96
	v_add_u32_e32 v33, 43, v130
	s_nop 0
	v_cndmask_b32_e32 v54, v187, v32, vcc
	v_add_f32_e32 v32, v97, v39
	v_sub_f32_e32 v32, v32, v55
	v_cmp_le_i32_e32 vcc, v33, v96
	s_nop 1
	v_cndmask_b32_e32 v55, v187, v32, vcc
	ds_read_b128 v[32:35], v104 offset:192
	v_max3_f32 v112, v36, v54, v55
	ds_read_b128 v[36:39], v104 offset:224
	v_cmp_le_i32_e32 vcc, v113, v96
	s_waitcnt lgkmcnt(1)
	v_sub_f32_e32 v32, v40, v32
	v_add_f32_e32 v40, v97, v41
	v_sub_f32_e32 v33, v40, v33
	v_add_u32_e32 v40, 49, v130
	v_add_f32_e32 v41, v97, v42
	v_cndmask_b32_e32 v32, v187, v32, vcc
	v_cmp_le_i32_e32 vcc, v40, v96
	v_sub_f32_e32 v34, v41, v34
	v_add_u32_e32 v41, 50, v130
	v_cndmask_b32_e32 v33, v187, v33, vcc
	v_cmp_le_i32_e32 vcc, v41, v96
	v_add_f32_e32 v41, v97, v43
	v_sub_f32_e32 v35, v41, v35
	v_add_u32_e32 v41, 51, v130
	v_cndmask_b32_e32 v34, v187, v34, vcc
	v_cmp_le_i32_e32 vcc, v41, v96
	v_add_u32_e32 v41, 56, v130
	v_add_f32_e32 v42, v97, v44
	v_cndmask_b32_e32 v35, v187, v35, vcc
	v_cmp_le_i32_e32 vcc, v41, v96
	v_add_f32_e32 v41, v97, v45
	s_waitcnt lgkmcnt(0)
	v_sub_f32_e32 v36, v42, v36
	v_sub_f32_e32 v37, v41, v37
	v_add_u32_e32 v41, 57, v130
	v_max3_f32 v40, v112, v32, v33
	v_cndmask_b32_e32 v36, v187, v36, vcc
	v_cmp_le_i32_e32 vcc, v41, v96
	v_max3_f32 v40, v40, v34, v35
	s_nop 0
	v_cndmask_b32_e32 v112, v187, v37, vcc
	v_max3_f32 v37, v40, v36, v112
	v_add_f32_e32 v40, v97, v46
	v_sub_f32_e32 v38, v40, v38
	v_add_u32_e32 v40, 58, v130
	v_cmp_le_i32_e32 vcc, v40, v96
	s_nop 1
	v_cndmask_b32_e32 v46, v187, v38, vcc
	v_add_f32_e32 v38, v97, v47
	v_sub_f32_e32 v38, v38, v39
	v_add_u32_e32 v39, 59, v130
	v_cmp_le_i32_e32 vcc, v39, v96
	s_nop 1
	v_cndmask_b32_e32 v47, v187, v38, vcc
	v_max3_f32 v37, v37, v46, v47
	ds_bpermute_b32 v38, v99, v37
	s_waitcnt lgkmcnt(0)
	v_max3_f32 v113, v105, v37, v38
	s_mov_b32 s99, 0x3fb8aa3b
	v_mul_f32_e32 v250, 0xbfb8aa3b, v113
	v_fma_f32 v38, v106, s99, v250
	v_exp_f32_e32 v38, v38
	v_fma_f32 v39, v107, s99, v250
	v_exp_f32_e32 v39, v39
	v_fma_f32 v40, v108, s99, v250
	v_exp_f32_e32 v40, v40
	v_fma_f32 v41, v109, s99, v250
	v_exp_f32_e32 v41, v41
	v_fma_f32 v43, v122, s99, v250
	v_add_f32_e32 v42, 0, v38
	v_exp_f32_e32 v43, v43
	v_fma_f32 v44, v123, s99, v250
	v_sub_f32_e32 v37, v105, v113
	v_add_f32_e32 v42, v39, v42
	v_exp_f32_e32 v44, v44
	v_fma_f32 v45, v110, s99, v250
	v_add_f32_e32 v42, v40, v42
	v_exp_f32_e32 v45, v45
	v_fma_f32 v105, v111, s99, v250
	v_add_f32_e32 v42, v41, v42
	v_exp_f32_e32 v105, v105
	v_fma_f32 v56, v56, s99, v250
	v_add_f32_e32 v42, v43, v42
	v_exp_f32_e32 v56, v56
	v_fma_f32 v57, v57, s99, v250
	v_add_f32_e32 v42, v44, v42
	v_exp_f32_e32 v57, v57
	v_fma_f32 v58, v58, s99, v250
	v_add_f32_e32 v42, v45, v42
	v_exp_f32_e32 v58, v58
	v_fma_f32 v59, v59, s99, v250
	v_add_f32_e32 v42, v105, v42
	v_exp_f32_e32 v59, v59
	v_fma_f32 v60, v60, s99, v250
	v_add_f32_e32 v42, v56, v42
	v_exp_f32_e32 v60, v60
	v_fma_f32 v61, v61, s99, v250
	v_add_f32_e32 v42, v57, v42
	v_exp_f32_e32 v61, v61
	v_fma_f32 v62, v62, s99, v250
	v_add_f32_e32 v42, v58, v42
	v_exp_f32_e32 v62, v62
	v_fma_f32 v63, v63, s99, v250
	v_add_f32_e32 v42, v59, v42
	v_exp_f32_e32 v63, v63
	v_add_f32_e32 v42, v60, v42
	v_add_f32_e32 v42, v61, v42
	v_add_f32_e32 v42, v62, v42
	v_add_f32_e32 v106, v63, v42
	v_fma_f32 v42, v48, s99, v250
	v_exp_f32_e32 v48, v42
	v_fma_f32 v32, v32, s99, v250
	v_fma_f32 v42, v49, s99, v250
	v_exp_f32_e32 v107, v32
	v_exp_f32_e32 v49, v42
	v_fma_f32 v32, v33, s99, v250
	v_fma_f32 v42, v50, s99, v250
	v_exp_f32_e32 v33, v32
	v_exp_f32_e32 v50, v42
	v_fma_f32 v32, v34, s99, v250
	v_fma_f32 v42, v51, s99, v250
	v_exp_f32_e32 v108, v32
	v_mul_f32_e32 v37, 0x3fb8aa3b, v37
	v_exp_f32_e32 v51, v42
	v_fma_f32 v32, v35, s99, v250
	v_fma_f32 v34, v36, s99, v250
	v_fma_f32 v42, v52, s99, v250
	v_exp_f32_e32 v109, v32
	v_exp_f32_e32 v32, v37
	v_exp_f32_e32 v110, v34
	ds_read2_b64 v[34:37], v102 offset0:128 offset1:130
	v_exp_f32_e32 v52, v42
	v_fma_f32 v42, v53, s99, v250
	v_exp_f32_e32 v53, v42
	v_fma_f32 v42, v54, s99, v250
	v_exp_f32_e32 v54, v42
	v_fma_f32 v42, v55, s99, v250
	v_exp_f32_e32 v55, v42
	v_cvt_pk_bf16_f32 v38, v38, v39
	v_cvt_pk_bf16_f32 v39, v40, v41
	v_cvt_pk_bf16_f32 v40, v43, v44
	v_cvt_pk_bf16_f32 v41, v45, v105
	ds_read2_b64 v[42:45], v103 offset0:192 offset1:194
	v_pk_mul_f32 v[30:31], v[30:31], v[32:33] op_sel_hi:[1,0]
	v_pk_mul_f32 v[28:29], v[28:29], v[32:33] op_sel_hi:[1,0]
	v_pk_mul_f32 v[26:27], v[26:27], v[32:33] op_sel_hi:[1,0]
	v_pk_mul_f32 v[24:25], v[24:25], v[32:33] op_sel_hi:[1,0]
	v_pk_mul_f32 v[22:23], v[22:23], v[32:33] op_sel_hi:[1,0]
	v_pk_mul_f32 v[20:21], v[20:21], v[32:33] op_sel_hi:[1,0]
	v_pk_mul_f32 v[18:19], v[18:19], v[32:33] op_sel_hi:[1,0]
	v_pk_mul_f32 v[16:17], v[16:17], v[32:33] op_sel_hi:[1,0]
	v_pk_mul_f32 v[14:15], v[14:15], v[32:33] op_sel_hi:[1,0]
	v_pk_mul_f32 v[12:13], v[12:13], v[32:33] op_sel_hi:[1,0]
	s_waitcnt lgkmcnt(1)
	v_mfma_f32_32x32x16_bf16 v[16:31], v[34:37], v[38:41], v[16:31]
	ds_read2_b64 v[34:37], v102 offset0:132 offset1:134
	v_mul_f32_e64 v10, v10, v32
	v_mul_f32_e64 v11, v11, v32
	v_mul_f32_e64 v8, v8, v32
	v_mul_f32_e64 v9, v9, v32
	v_pk_mul_f32 v[6:7], v[6:7], v[32:33] op_sel_hi:[1,0]
	v_pk_mul_f32 v[4:5], v[4:5], v[32:33] op_sel_hi:[1,0]
	v_pk_mul_f32 v[2:3], v[2:3], v[32:33] op_sel_hi:[1,0]
	v_pk_mul_f32 v[0:1], v[0:1], v[32:33] op_sel_hi:[1,0]
	s_waitcnt lgkmcnt(1)
	s_nop 0
	v_mfma_f32_32x32x16_bf16 v[0:15], v[42:45], v[38:41], v[0:15]
	v_fma_f32 v105, v112, s99, v250
	v_cvt_pk_bf16_f32 v38, v56, v57
	v_cvt_pk_bf16_f32 v39, v58, v59
	v_cvt_pk_bf16_f32 v40, v60, v61
	v_cvt_pk_bf16_f32 v41, v62, v63
	ds_read2_b64 v[42:45], v103 offset0:196 offset1:198
	v_add_f32_e32 v57, v48, v106
	s_waitcnt lgkmcnt(1)
	v_mfma_f32_32x32x16_bf16 v[16:31], v[34:37], v[38:41], v[16:31]
	v_fma_f32 v34, v46, s99, v250
	v_exp_f32_e32 v46, v34
	v_fma_f32 v47, v47, s99, v250
	ds_read2_b64 v[34:37], v102 offset0:136 offset1:138
	v_exp_f32_e32 v56, v105
	s_waitcnt lgkmcnt(1)
	v_mfma_f32_32x32x16_bf16 v[0:15], v[42:45], v[38:41], v[0:15]
	ds_read2_b64 v[42:45], v103 offset0:200 offset1:202
	v_cvt_pk_bf16_f32 v38, v48, v49
	v_cvt_pk_bf16_f32 v39, v50, v51
	v_cvt_pk_bf16_f32 v40, v52, v53
	v_cvt_pk_bf16_f32 v41, v54, v55
	v_exp_f32_e32 v47, v47
	v_mov_b32_e32 v105, v113
	s_waitcnt lgkmcnt(1)
	v_mfma_f32_32x32x16_bf16 v[16:31], v[34:37], v[38:41], v[16:31]
	v_add_f32_e32 v34, v49, v57
	v_add_f32_e32 v34, v50, v34
	v_add_f32_e32 v34, v51, v34
	v_add_f32_e32 v34, v52, v34
	v_add_f32_e32 v34, v53, v34
	v_add_f32_e32 v48, v54, v34
	ds_read2_b64 v[34:37], v102 offset0:140 offset1:142
	s_waitcnt lgkmcnt(1)
	v_mfma_f32_32x32x16_bf16 v[0:15], v[42:45], v[38:41], v[0:15]
	ds_read2_b64 v[42:45], v103 offset0:204 offset1:206
	v_add_f32_e32 v38, v55, v48
	v_add_f32_e32 v48, v107, v38
	v_cvt_pk_bf16_f32 v38, v107, v33
	v_cvt_pk_bf16_f32 v39, v108, v109
	v_cvt_pk_bf16_f32 v40, v110, v56
	v_cvt_pk_bf16_f32 v41, v46, v47
	v_add_f32_e32 v33, v33, v48
	v_add_f32_e32 v33, v108, v33
	s_waitcnt lgkmcnt(1)
	v_mfma_f32_32x32x16_bf16 v[16:31], v[34:37], v[38:41], v[16:31]
	v_add_f32_e32 v33, v109, v33
	v_add_f32_e32 v33, v110, v33
	v_add_f32_e32 v33, v56, v33
	v_add_f32_e32 v33, v46, v33
	v_add_f32_e32 v33, v47, v33
	v_fmac_f32_e32 v33, v100, v32
	v_mov_b32_e32 v100, v33
	s_waitcnt lgkmcnt(0)
	v_mfma_f32_32x32x16_bf16 v[0:15], v[42:45], v[38:41], v[0:15]
	s_branch .LBB0_934
